# grid barrier acquire by wave 0: non-last arrivers invalidate L1 right after their arrival count returns; the XCD's last arriver issues the invalidate directly behind its L2 writeback so both complete
# speedup vs baseline: 1.0013x; 1.0013x over previous
.Lgb_have_counts:
	s_add_i32 s12, s9, 1
	s_mul_i32 s13, s10, s12
	s_mul_i32 s14, s11, s12
	s_lshl_b32 s15, s8, 8
	s_add_u32 s16, s6, s15
	s_addc_u32 s17, s7, 0
	s_add_u32 s16, s16, 0x1400
	s_addc_u32 s17, s17, 0
	global_atomic_add v3, v1, v2, s[16:17] sc0
	s_waitcnt vmcnt(0)
	v_readfirstlane_b32 s15, v3
	s_add_i32 s15, s15, 1
	s_cmp_lg_u32 s15, s13
	s_cbranch_scc0 .Lgb_last
	buffer_inv sc1
	s_branch .Lgb_wait
.Lgb_last:
	buffer_wbl2 sc1
	buffer_inv sc1
	s_waitcnt vmcnt(0)
	global_atomic_add v1, v2, s[18:19]
	s_branch .Lgb_wait
	s_cbranch_scc1 .Lgb_wait
	buffer_wbl2 sc1
	s_waitcnt vmcnt(0)
	global_atomic_add v1, v2, s[18:19]
